# PEER pass V loop top: first expert row's 16 fp4 conversions issued together behind the coefficient LDS reads
# speedup vs baseline: 1.0003x; 1.0003x over previous
; __device__ __forceinline__ void p8_peer_gather(Frame& F) {
;     ...
;             const f32x4 c0 = *(const f32x4*)(cf_s + j * 128 + pg * 16), c1 = *(const f32x4*)(cf_s + j * 128 + pg * 16 + 4), c2 = *(const f32x4*)(cf_s + j * 128 + pg * 16 + 8), c3 = *(const f32x4*)(cf_s + j * 128 + pg * 16 + 12);
;             const float cc[16] = {c0[0], c0[1], c0[2], c0[3], c1[0], c1[1], c1[2], c1[3], c2[0], c2[1], c2[2], c2[3], c3[0], c3[1], c3[2], c3[3]};
;             h16x2 ya[16];
; #pragma unroll
;             for (int e = 0; e < 16; ++e) ya[e] = (h16x2){(_Float16)0.f, (_Float16)0.f};
; #pragma unroll
;             for (int i = 0; i < 16; ++i) { const h16x2 cf2 = __builtin_bit_cast(h16x2, cc[i]);
; #pragma unroll
;                 for (int w = 0; w < 4; ++w) { ya[4 * w] += cf2 * __builtin_amdgcn_cvt_scalef32_pk_f16_fp4(d[i][w], 1.0f, 0); ya[4 * w + 1] += cf2 * __builtin_amdgcn_cvt_scalef32_pk_f16_fp4(d[i][w], 1.0f, 1);
;                     ya[4 * w + 2] += cf2 * __builtin_amdgcn_cvt_scalef32_pk_f16_fp4(d[i][w], 1.0f, 2); ya[4 * w + 3] += cf2 * __builtin_amdgcn_cvt_scalef32_pk_f16_fp4(d[i][w], 1.0f, 3); }
;                 d[i] = *(const v4u*)(VQ + (size_t)(idx_s[nj * 128 + pg * 16 + i] + noff)); }
.LBB0_2586:
	s_min_i32 s28, s14, 64
	s_add_i32 s14, s14, 8
	s_cmp_ge_u32 s14, s17
	s_cselect_b64 s[20:21], -1, 0
	s_and_b64 s[22:23], s[18:19], exec
	s_cselect_b32 s29, s28, s74
	s_min_i32 s30, s14, 64
	s_cmp_lt_u32 s14, s17
	s_cselect_b64 s[22:23], -1, 0
	s_and_b64 s[24:25], s[22:23], exec
	s_cselect_b32 s24, s30, s29
	s_or_b64 s[22:23], s[18:19], s[22:23]
	s_and_b64 s[22:23], s[22:23], exec
	s_cselect_b32 s25, s26, s27
	s_lshl_b32 s22, s28, 8
	s_add_u32 s22, s22, s72
	s_addc_u32 s23, 0, s73
	s_lshl_b64 s[22:23], s[22:23], 13
	v_lshl_add_u64 v[88:89], v[86:87], 0, s[22:23]
	v_lshl_add_u32 v64, s28, 9, v94
	global_load_dwordx2 v[90:91], v[88:89], off
	ds_read_b128 v[98:101], v64 offset:33280
	ds_read_b128 v[80:83], v64 offset:33296
	ds_read_b128 v[72:75], v64 offset:33312
	ds_read_b128 v[64:67], v64 offset:33328
	s_waitcnt vmcnt(16)
	v_cvt_scalef32_pk_f16_fp4 v68, v24, 1.0
	v_cvt_scalef32_pk_f16_fp4 v69, v24, 1.0 op_sel:[1,0,0]
	v_cvt_scalef32_pk_f16_fp4 v70, v24, 1.0 op_sel:[0,1,0]
	v_cvt_scalef32_pk_f16_fp4 v24, v24, 1.0 op_sel:[1,1,0]
	v_cvt_scalef32_pk_f16_fp4 v71, v25, 1.0
	v_cvt_scalef32_pk_f16_fp4 v76, v25, 1.0 op_sel:[1,0,0]
	v_cvt_scalef32_pk_f16_fp4 v77, v25, 1.0 op_sel:[0,1,0]
	v_cvt_scalef32_pk_f16_fp4 v25, v25, 1.0 op_sel:[1,1,0]
	v_cvt_scalef32_pk_f16_fp4 v78, v26, 1.0
	v_cvt_scalef32_pk_f16_fp4 v79, v26, 1.0 op_sel:[1,0,0]
	v_cvt_scalef32_pk_f16_fp4 v97, v26, 1.0 op_sel:[0,1,0]
	v_cvt_scalef32_pk_f16_fp4 v26, v26, 1.0 op_sel:[1,1,0]
	v_cvt_scalef32_pk_f16_fp4 v102, v27, 1.0
	v_cvt_scalef32_pk_f16_fp4 v103, v27, 1.0 op_sel:[1,0,0]
	v_cvt_scalef32_pk_f16_fp4 v104, v27, 1.0 op_sel:[0,1,0]
	v_cvt_scalef32_pk_f16_fp4 v27, v27, 1.0 op_sel:[1,1,0]
	s_waitcnt lgkmcnt(3)
	v_pk_fma_f16 v68, v68, v98, 0
	s_waitcnt vmcnt(15)
	v_cvt_scalef32_pk_f16_fp4 v105, v0, 1.0
	v_pk_fma_f16 v69, v69, v98, 0
	v_pk_fma_f16 v110, v105, v99, v68
	v_cvt_scalef32_pk_f16_fp4 v68, v0, 1.0 op_sel:[1,0,0]
	v_pk_fma_f16 v24, v24, v98, 0
	v_pk_fma_f16 v111, v68, v99, v69
	v_cvt_scalef32_pk_f16_fp4 v68, v0, 1.0 op_sel:[0,1,0]
	v_cvt_scalef32_pk_f16_fp4 v0, v0, 1.0 op_sel:[1,1,0]
	v_pk_fma_f16 v71, v71, v98, 0
	v_pk_fma_f16 v113, v0, v99, v24
	v_cvt_scalef32_pk_f16_fp4 v0, v1, 1.0
	v_pk_fma_f16 v76, v76, v98, 0
	v_pk_fma_f16 v114, v0, v99, v71
	v_cvt_scalef32_pk_f16_fp4 v0, v1, 1.0 op_sel:[1,0,0]
	v_pk_fma_f16 v77, v77, v98, 0
	v_pk_fma_f16 v115, v0, v99, v76
	v_cvt_scalef32_pk_f16_fp4 v0, v1, 1.0 op_sel:[0,1,0]
	v_pk_fma_f16 v25, v25, v98, 0
	v_pk_fma_f16 v116, v0, v99, v77
	v_cvt_scalef32_pk_f16_fp4 v0, v1, 1.0 op_sel:[1,1,0]
	v_pk_fma_f16 v78, v78, v98, 0
	v_pk_fma_f16 v117, v0, v99, v25
	v_cvt_scalef32_pk_f16_fp4 v0, v2, 1.0
	v_pk_fma_f16 v79, v79, v98, 0
	v_pk_fma_f16 v118, v0, v99, v78
	v_cvt_scalef32_pk_f16_fp4 v0, v2, 1.0 op_sel:[1,0,0]
	v_pk_fma_f16 v97, v97, v98, 0
	v_pk_fma_f16 v119, v0, v99, v79
	v_cvt_scalef32_pk_f16_fp4 v0, v2, 1.0 op_sel:[0,1,0]
	v_pk_fma_f16 v26, v26, v98, 0
	v_pk_fma_f16 v97, v0, v99, v97
	v_cvt_scalef32_pk_f16_fp4 v0, v2, 1.0 op_sel:[1,1,0]
	v_pk_fma_f16 v102, v102, v98, 0
	v_pk_fma_f16 v120, v0, v99, v26
	v_cvt_scalef32_pk_f16_fp4 v0, v3, 1.0
	v_pk_fma_f16 v103, v103, v98, 0
	v_pk_fma_f16 v121, v0, v99, v102
	v_cvt_scalef32_pk_f16_fp4 v0, v3, 1.0 op_sel:[1,0,0]
	v_pk_fma_f16 v70, v70, v98, 0
	v_pk_fma_f16 v104, v104, v98, 0
	v_pk_fma_f16 v27, v27, v98, 0
	v_lshl_add_u32 v98, s24, 9, v94
	v_pk_fma_f16 v122, v0, v99, v103
	v_cvt_scalef32_pk_f16_fp4 v0, v3, 1.0 op_sel:[0,1,0]
	v_pk_fma_f16 v123, v0, v99, v104
	ds_read_b128 v[102:105], v98
	v_or_b32_e32 v96, s25, v93
	v_cvt_scalef32_pk_f16_fp4 v0, v3, 1.0 op_sel:[1,1,0]
	v_pk_fma_f16 v112, v68, v99, v70
	v_pk_fma_f16 v99, v0, v99, v27
	s_waitcnt lgkmcnt(0)
	v_add_u32_e32 v102, v102, v96
	ds_read_b128 v[106:109], v98 offset:16
	ds_read_b128 v[76:79], v98 offset:32
	ds_read_b128 v[68:71], v98 offset:48
	v_add_u32_e32 v98, v103, v96
	global_load_dwordx4 v[24:27], v102, s[12:13]
	global_load_dwordx4 v[0:3], v98, s[12:13]
	s_waitcnt vmcnt(16)
	v_cvt_scalef32_pk_f16_fp4 v102, v28, 1.0 op_sel:[1,0,0]
	v_cvt_scalef32_pk_f16_fp4 v98, v28, 1.0
	v_pk_fma_f16 v102, v102, v100, v111
	v_cvt_scalef32_pk_f16_fp4 v103, v28, 1.0 op_sel:[0,1,0]
	v_cvt_scalef32_pk_f16_fp4 v111, v29, 1.0 op_sel:[1,0,0]
	v_pk_fma_f16 v98, v98, v100, v110
	v_pk_fma_f16 v103, v103, v100, v112
	v_cvt_scalef32_pk_f16_fp4 v110, v29, 1.0
	v_pk_fma_f16 v111, v111, v100, v115
	v_cvt_scalef32_pk_f16_fp4 v112, v29, 1.0 op_sel:[0,1,0]
	v_cvt_scalef32_pk_f16_fp4 v29, v29, 1.0 op_sel:[1,1,0]
	v_cvt_scalef32_pk_f16_fp4 v115, v30, 1.0 op_sel:[0,1,0]
	v_cvt_scalef32_pk_f16_fp4 v28, v28, 1.0 op_sel:[1,1,0]
	v_pk_fma_f16 v112, v112, v100, v116
	v_pk_fma_f16 v29, v29, v100, v117
	v_pk_fma_f16 v97, v115, v100, v97
	v_cvt_scalef32_pk_f16_fp4 v115, v31, 1.0
	v_cvt_scalef32_pk_f16_fp4 v116, v31, 1.0 op_sel:[1,0,0]
	v_cvt_scalef32_pk_f16_fp4 v117, v31, 1.0 op_sel:[0,1,0]
	v_cvt_scalef32_pk_f16_fp4 v31, v31, 1.0 op_sel:[1,1,0]
	v_pk_fma_f16 v28, v28, v100, v113
	v_pk_fma_f16 v110, v110, v100, v114
	v_cvt_scalef32_pk_f16_fp4 v113, v30, 1.0
	v_cvt_scalef32_pk_f16_fp4 v114, v30, 1.0 op_sel:[1,0,0]
	v_cvt_scalef32_pk_f16_fp4 v30, v30, 1.0 op_sel:[1,1,0]
	v_pk_fma_f16 v31, v31, v100, v99
	s_waitcnt vmcnt(15)
; __device__ __forceinline__ void p8_peer_gather(Frame& F) {
;     ...
;             for (int i = 0; i < 16; ++i) { const h16x2 cf2 = __builtin_bit_cast(h16x2, cc[i]);
; #pragma unroll
;                 for (int w = 0; w < 4; ++w) { ya[4 * w] += cf2 * __builtin_amdgcn_cvt_scalef32_pk_f16_fp4(d[i][w], 1.0f, 0); ya[4 * w + 1] += cf2 * __builtin_amdgcn_cvt_scalef32_pk_f16_fp4(d[i][w], 1.0f, 1);
;                     ya[4 * w + 2] += cf2 * __builtin_amdgcn_cvt_scalef32_pk_f16_fp4(d[i][w], 1.0f, 2); ya[4 * w + 3] += cf2 * __builtin_amdgcn_cvt_scalef32_pk_f16_fp4(d[i][w], 1.0f, 3); }
;                 d[i] = *(const v4u*)(VQ + (size_t)(idx_s[nj * 128 + pg * 16 + i] + noff)); }
	v_cvt_scalef32_pk_f16_fp4 v99, v4, 1.0
	v_pk_fma_f16 v113, v113, v100, v118
	v_pk_fma_f16 v114, v114, v100, v119
	v_pk_fma_f16 v30, v30, v100, v120
	v_pk_fma_f16 v115, v115, v100, v121
	v_pk_fma_f16 v116, v116, v100, v122
	v_pk_fma_f16 v117, v117, v100, v123
	v_pk_fma_f16 v98, v99, v101, v98
	v_cvt_scalef32_pk_f16_fp4 v99, v4, 1.0 op_sel:[1,0,0]
	v_cvt_scalef32_pk_f16_fp4 v100, v4, 1.0 op_sel:[0,1,0]
	v_cvt_scalef32_pk_f16_fp4 v4, v4, 1.0 op_sel:[1,1,0]
	v_pk_fma_f16 v99, v99, v101, v102
	v_pk_fma_f16 v102, v4, v101, v28
	v_cvt_scalef32_pk_f16_fp4 v4, v5, 1.0
	v_pk_fma_f16 v100, v100, v101, v103
	v_pk_fma_f16 v103, v4, v101, v110
	v_cvt_scalef32_pk_f16_fp4 v4, v5, 1.0 op_sel:[1,0,0]
	v_pk_fma_f16 v110, v4, v101, v111
	v_cvt_scalef32_pk_f16_fp4 v4, v5, 1.0 op_sel:[0,1,0]
	v_pk_fma_f16 v111, v4, v101, v112
	v_cvt_scalef32_pk_f16_fp4 v4, v5, 1.0 op_sel:[1,1,0]
	v_pk_fma_f16 v112, v4, v101, v29
	v_cvt_scalef32_pk_f16_fp4 v4, v6, 1.0
	v_pk_fma_f16 v113, v4, v101, v113
	v_cvt_scalef32_pk_f16_fp4 v4, v6, 1.0 op_sel:[1,0,0]
	v_pk_fma_f16 v114, v4, v101, v114
	v_cvt_scalef32_pk_f16_fp4 v4, v6, 1.0 op_sel:[0,1,0]
	v_pk_fma_f16 v97, v4, v101, v97
	v_cvt_scalef32_pk_f16_fp4 v4, v6, 1.0 op_sel:[1,1,0]
	v_pk_fma_f16 v118, v4, v101, v30
	v_cvt_scalef32_pk_f16_fp4 v4, v7, 1.0
	v_pk_fma_f16 v115, v4, v101, v115
	v_cvt_scalef32_pk_f16_fp4 v4, v7, 1.0 op_sel:[1,0,0]
	v_pk_fma_f16 v116, v4, v101, v116
	v_cvt_scalef32_pk_f16_fp4 v4, v7, 1.0 op_sel:[0,1,0]
	v_pk_fma_f16 v117, v4, v101, v117
	v_cvt_scalef32_pk_f16_fp4 v4, v7, 1.0 op_sel:[1,1,0]
	v_add_u32_e32 v104, v104, v96
	v_pk_fma_f16 v101, v4, v101, v31
	v_add_u32_e32 v105, v105, v96
	global_load_dwordx4 v[28:31], v104, s[12:13]
	global_load_dwordx4 v[4:7], v105, s[12:13]
	s_waitcnt vmcnt(16)
	v_cvt_scalef32_pk_f16_fp4 v104, v36, 1.0
	v_pk_fma_f16 v98, v104, v80, v98
	v_cvt_scalef32_pk_f16_fp4 v104, v36, 1.0 op_sel:[1,0,0]
	v_pk_fma_f16 v99, v104, v80, v99
	v_cvt_scalef32_pk_f16_fp4 v104, v36, 1.0 op_sel:[0,1,0]
	v_cvt_scalef32_pk_f16_fp4 v36, v36, 1.0 op_sel:[1,1,0]
	v_pk_fma_f16 v100, v104, v80, v100
	v_pk_fma_f16 v36, v36, v80, v102
	v_cvt_scalef32_pk_f16_fp4 v102, v37, 1.0
	v_cvt_scalef32_pk_f16_fp4 v104, v37, 1.0 op_sel:[0,1,0]
	v_pk_fma_f16 v102, v102, v80, v103
	v_cvt_scalef32_pk_f16_fp4 v103, v37, 1.0 op_sel:[1,0,0]
	v_pk_fma_f16 v104, v104, v80, v111
	v_cvt_scalef32_pk_f16_fp4 v37, v37, 1.0 op_sel:[1,1,0]
	v_cvt_scalef32_pk_f16_fp4 v105, v38, 1.0
	v_cvt_scalef32_pk_f16_fp4 v111, v38, 1.0 op_sel:[0,1,0]
	v_pk_fma_f16 v103, v103, v80, v110
	v_pk_fma_f16 v37, v37, v80, v112
	v_pk_fma_f16 v105, v105, v80, v113
	v_cvt_scalef32_pk_f16_fp4 v110, v38, 1.0 op_sel:[1,0,0]
	v_pk_fma_f16 v97, v111, v80, v97
	v_cvt_scalef32_pk_f16_fp4 v38, v38, 1.0 op_sel:[1,1,0]
	v_cvt_scalef32_pk_f16_fp4 v111, v39, 1.0
	v_cvt_scalef32_pk_f16_fp4 v112, v39, 1.0 op_sel:[1,0,0]
	v_cvt_scalef32_pk_f16_fp4 v113, v39, 1.0 op_sel:[0,1,0]
	v_cvt_scalef32_pk_f16_fp4 v39, v39, 1.0 op_sel:[1,1,0]
	v_pk_fma_f16 v110, v110, v80, v114
	v_pk_fma_f16 v38, v38, v80, v118
	v_pk_fma_f16 v111, v111, v80, v115
	v_pk_fma_f16 v112, v112, v80, v116
	v_pk_fma_f16 v113, v113, v80, v117
	v_pk_fma_f16 v39, v39, v80, v101
	s_waitcnt vmcnt(15)
	v_cvt_scalef32_pk_f16_fp4 v80, v8, 1.0
	v_pk_fma_f16 v80, v80, v81, v98
	v_cvt_scalef32_pk_f16_fp4 v98, v8, 1.0 op_sel:[1,0,0]
	v_pk_fma_f16 v98, v98, v81, v99
	v_cvt_scalef32_pk_f16_fp4 v99, v8, 1.0 op_sel:[0,1,0]
	v_cvt_scalef32_pk_f16_fp4 v8, v8, 1.0 op_sel:[1,1,0]
	v_pk_fma_f16 v99, v99, v81, v100
	v_pk_fma_f16 v100, v8, v81, v36
	v_cvt_scalef32_pk_f16_fp4 v8, v9, 1.0
	v_pk_fma_f16 v101, v8, v81, v102
	v_cvt_scalef32_pk_f16_fp4 v8, v9, 1.0 op_sel:[1,0,0]
	v_pk_fma_f16 v102, v8, v81, v103
	v_cvt_scalef32_pk_f16_fp4 v8, v9, 1.0 op_sel:[0,1,0]
	v_pk_fma_f16 v103, v8, v81, v104
	v_cvt_scalef32_pk_f16_fp4 v8, v9, 1.0 op_sel:[1,1,0]
	v_pk_fma_f16 v104, v8, v81, v37
	v_cvt_scalef32_pk_f16_fp4 v8, v10, 1.0
	v_pk_fma_f16 v105, v8, v81, v105
	v_cvt_scalef32_pk_f16_fp4 v8, v10, 1.0 op_sel:[1,0,0]
	v_pk_fma_f16 v110, v8, v81, v110
	v_cvt_scalef32_pk_f16_fp4 v8, v10, 1.0 op_sel:[0,1,0]
	v_pk_fma_f16 v97, v8, v81, v97
	v_cvt_scalef32_pk_f16_fp4 v8, v10, 1.0 op_sel:[1,1,0]
	v_pk_fma_f16 v114, v8, v81, v38
	v_cvt_scalef32_pk_f16_fp4 v8, v11, 1.0
	v_pk_fma_f16 v111, v8, v81, v111
	v_cvt_scalef32_pk_f16_fp4 v8, v11, 1.0 op_sel:[1,0,0]
	v_pk_fma_f16 v112, v8, v81, v112
	v_cvt_scalef32_pk_f16_fp4 v8, v11, 1.0 op_sel:[0,1,0]
	v_pk_fma_f16 v113, v8, v81, v113
	v_cvt_scalef32_pk_f16_fp4 v8, v11, 1.0 op_sel:[1,1,0]
	s_waitcnt lgkmcnt(2)
	v_add_u32_e32 v106, v106, v96
	v_pk_fma_f16 v81, v8, v81, v39
	v_add_u32_e32 v107, v107, v96
	global_load_dwordx4 v[36:39], v106, s[12:13]
	global_load_dwordx4 v[8:11], v107, s[12:13]
	s_waitcnt vmcnt(16)
	v_cvt_scalef32_pk_f16_fp4 v106, v44, 1.0
	v_pk_fma_f16 v80, v106, v82, v80
	v_cvt_scalef32_pk_f16_fp4 v106, v44, 1.0 op_sel:[1,0,0]
	v_pk_fma_f16 v98, v106, v82, v98
	v_cvt_scalef32_pk_f16_fp4 v106, v44, 1.0 op_sel:[0,1,0]
	v_cvt_scalef32_pk_f16_fp4 v44, v44, 1.0 op_sel:[1,1,0]
	v_pk_fma_f16 v44, v44, v82, v100
	v_cvt_scalef32_pk_f16_fp4 v100, v45, 1.0
	v_pk_fma_f16 v100, v100, v82, v101
	v_cvt_scalef32_pk_f16_fp4 v101, v45, 1.0 op_sel:[1,0,0]
	v_pk_fma_f16 v101, v101, v82, v102
	v_cvt_scalef32_pk_f16_fp4 v102, v45, 1.0 op_sel:[0,1,0]
	v_pk_fma_f16 v102, v102, v82, v103
	v_cvt_scalef32_pk_f16_fp4 v103, v46, 1.0
	v_pk_fma_f16 v103, v103, v82, v105
	v_cvt_scalef32_pk_f16_fp4 v105, v46, 1.0 op_sel:[0,1,0]
	v_pk_fma_f16 v99, v106, v82, v99
	v_cvt_scalef32_pk_f16_fp4 v45, v45, 1.0 op_sel:[1,1,0]
	v_pk_fma_f16 v97, v105, v82, v97
	v_cvt_scalef32_pk_f16_fp4 v105, v47, 1.0
	v_cvt_scalef32_pk_f16_fp4 v106, v47, 1.0 op_sel:[1,0,0]
	v_cvt_scalef32_pk_f16_fp4 v107, v47, 1.0 op_sel:[0,1,0]
	v_cvt_scalef32_pk_f16_fp4 v47, v47, 1.0 op_sel:[1,1,0]
	v_pk_fma_f16 v45, v45, v82, v104
	v_cvt_scalef32_pk_f16_fp4 v104, v46, 1.0 op_sel:[1,0,0]
	v_cvt_scalef32_pk_f16_fp4 v46, v46, 1.0 op_sel:[1,1,0]
	v_pk_fma_f16 v47, v47, v82, v81
	s_waitcnt vmcnt(15)
; __device__ __forceinline__ void p8_peer_gather(Frame& F) {
;     ...
;             for (int i = 0; i < 16; ++i) { const h16x2 cf2 = __builtin_bit_cast(h16x2, cc[i]);
; #pragma unroll
;                 for (int w = 0; w < 4; ++w) { ya[4 * w] += cf2 * __builtin_amdgcn_cvt_scalef32_pk_f16_fp4(d[i][w], 1.0f, 0); ya[4 * w + 1] += cf2 * __builtin_amdgcn_cvt_scalef32_pk_f16_fp4(d[i][w], 1.0f, 1);
;                     ya[4 * w + 2] += cf2 * __builtin_amdgcn_cvt_scalef32_pk_f16_fp4(d[i][w], 1.0f, 2); ya[4 * w + 3] += cf2 * __builtin_amdgcn_cvt_scalef32_pk_f16_fp4(d[i][w], 1.0f, 3); }
;                 d[i] = *(const v4u*)(VQ + (size_t)(idx_s[nj * 128 + pg * 16 + i] + noff)); }
	v_cvt_scalef32_pk_f16_fp4 v81, v12, 1.0
	v_pk_fma_f16 v104, v104, v82, v110
	v_pk_fma_f16 v46, v46, v82, v114
	v_pk_fma_f16 v105, v105, v82, v111
	v_pk_fma_f16 v106, v106, v82, v112
	v_pk_fma_f16 v107, v107, v82, v113
	v_pk_fma_f16 v80, v81, v83, v80
	v_cvt_scalef32_pk_f16_fp4 v81, v12, 1.0 op_sel:[1,0,0]
	v_cvt_scalef32_pk_f16_fp4 v82, v12, 1.0 op_sel:[0,1,0]
	v_cvt_scalef32_pk_f16_fp4 v12, v12, 1.0 op_sel:[1,1,0]
	v_pk_fma_f16 v81, v81, v83, v98
	v_pk_fma_f16 v98, v12, v83, v44
	v_cvt_scalef32_pk_f16_fp4 v12, v13, 1.0
	v_pk_fma_f16 v82, v82, v83, v99
	v_pk_fma_f16 v99, v12, v83, v100
	v_cvt_scalef32_pk_f16_fp4 v12, v13, 1.0 op_sel:[1,0,0]
	v_pk_fma_f16 v100, v12, v83, v101
	v_cvt_scalef32_pk_f16_fp4 v12, v13, 1.0 op_sel:[0,1,0]
	v_pk_fma_f16 v101, v12, v83, v102
	v_cvt_scalef32_pk_f16_fp4 v12, v13, 1.0 op_sel:[1,1,0]
	v_pk_fma_f16 v102, v12, v83, v45
	v_cvt_scalef32_pk_f16_fp4 v12, v14, 1.0
	v_pk_fma_f16 v103, v12, v83, v103
	v_cvt_scalef32_pk_f16_fp4 v12, v14, 1.0 op_sel:[1,0,0]
	v_pk_fma_f16 v104, v12, v83, v104
	v_cvt_scalef32_pk_f16_fp4 v12, v14, 1.0 op_sel:[0,1,0]
	v_pk_fma_f16 v97, v12, v83, v97
	v_cvt_scalef32_pk_f16_fp4 v12, v14, 1.0 op_sel:[1,1,0]
	v_pk_fma_f16 v110, v12, v83, v46
	v_cvt_scalef32_pk_f16_fp4 v12, v15, 1.0
	v_pk_fma_f16 v105, v12, v83, v105
	v_cvt_scalef32_pk_f16_fp4 v12, v15, 1.0 op_sel:[1,0,0]
	v_pk_fma_f16 v106, v12, v83, v106
	v_cvt_scalef32_pk_f16_fp4 v12, v15, 1.0 op_sel:[0,1,0]
	v_pk_fma_f16 v107, v12, v83, v107
	v_cvt_scalef32_pk_f16_fp4 v12, v15, 1.0 op_sel:[1,1,0]
	v_add_u32_e32 v108, v108, v96
	v_pk_fma_f16 v83, v12, v83, v47
	v_add_u32_e32 v109, v109, v96
	global_load_dwordx4 v[44:47], v108, s[12:13]
	global_load_dwordx4 v[12:15], v109, s[12:13]
	s_waitcnt vmcnt(16)
	v_cvt_scalef32_pk_f16_fp4 v108, v48, 1.0
	v_pk_fma_f16 v80, v108, v72, v80
	v_cvt_scalef32_pk_f16_fp4 v108, v48, 1.0 op_sel:[1,0,0]
	v_pk_fma_f16 v81, v108, v72, v81
	v_cvt_scalef32_pk_f16_fp4 v108, v48, 1.0 op_sel:[0,1,0]
	v_cvt_scalef32_pk_f16_fp4 v48, v48, 1.0 op_sel:[1,1,0]
	v_pk_fma_f16 v48, v48, v72, v98
	v_cvt_scalef32_pk_f16_fp4 v98, v49, 1.0
	v_pk_fma_f16 v98, v98, v72, v99
	v_cvt_scalef32_pk_f16_fp4 v99, v49, 1.0 op_sel:[1,0,0]
	v_pk_fma_f16 v99, v99, v72, v100
	v_cvt_scalef32_pk_f16_fp4 v100, v49, 1.0 op_sel:[0,1,0]
	v_pk_fma_f16 v100, v100, v72, v101
	v_cvt_scalef32_pk_f16_fp4 v101, v50, 1.0
	v_cvt_scalef32_pk_f16_fp4 v49, v49, 1.0 op_sel:[1,1,0]
	v_pk_fma_f16 v101, v101, v72, v103
	v_cvt_scalef32_pk_f16_fp4 v103, v50, 1.0 op_sel:[0,1,0]
	v_pk_fma_f16 v49, v49, v72, v102
	v_cvt_scalef32_pk_f16_fp4 v102, v50, 1.0 op_sel:[1,0,0]
	v_pk_fma_f16 v97, v103, v72, v97
	v_cvt_scalef32_pk_f16_fp4 v103, v51, 1.0
	v_pk_fma_f16 v102, v102, v72, v104
	v_cvt_scalef32_pk_f16_fp4 v50, v50, 1.0 op_sel:[1,1,0]
	v_pk_fma_f16 v103, v103, v72, v105
	v_cvt_scalef32_pk_f16_fp4 v104, v51, 1.0 op_sel:[1,0,0]
	v_cvt_scalef32_pk_f16_fp4 v105, v51, 1.0 op_sel:[0,1,0]
	v_cvt_scalef32_pk_f16_fp4 v51, v51, 1.0 op_sel:[1,1,0]
	v_pk_fma_f16 v82, v108, v72, v82
	v_pk_fma_f16 v50, v50, v72, v110
	v_pk_fma_f16 v104, v104, v72, v106
	v_pk_fma_f16 v105, v105, v72, v107
	v_pk_fma_f16 v51, v51, v72, v83
	s_waitcnt vmcnt(15)
	v_cvt_scalef32_pk_f16_fp4 v72, v16, 1.0
	v_pk_fma_f16 v72, v72, v73, v80
	v_cvt_scalef32_pk_f16_fp4 v80, v16, 1.0 op_sel:[1,0,0]
	v_pk_fma_f16 v80, v80, v73, v81
	v_cvt_scalef32_pk_f16_fp4 v81, v16, 1.0 op_sel:[0,1,0]
	v_cvt_scalef32_pk_f16_fp4 v16, v16, 1.0 op_sel:[1,1,0]
	v_pk_fma_f16 v81, v81, v73, v82
	v_pk_fma_f16 v82, v16, v73, v48
	v_cvt_scalef32_pk_f16_fp4 v16, v17, 1.0
	v_pk_fma_f16 v83, v16, v73, v98
	v_cvt_scalef32_pk_f16_fp4 v16, v17, 1.0 op_sel:[1,0,0]
	v_pk_fma_f16 v98, v16, v73, v99
	v_cvt_scalef32_pk_f16_fp4 v16, v17, 1.0 op_sel:[0,1,0]
	v_pk_fma_f16 v99, v16, v73, v100
	v_cvt_scalef32_pk_f16_fp4 v16, v17, 1.0 op_sel:[1,1,0]
	v_pk_fma_f16 v100, v16, v73, v49
	v_cvt_scalef32_pk_f16_fp4 v16, v18, 1.0
	v_pk_fma_f16 v101, v16, v73, v101
	v_cvt_scalef32_pk_f16_fp4 v16, v18, 1.0 op_sel:[1,0,0]
	v_pk_fma_f16 v102, v16, v73, v102
	v_cvt_scalef32_pk_f16_fp4 v16, v18, 1.0 op_sel:[0,1,0]
	v_pk_fma_f16 v97, v16, v73, v97
	v_cvt_scalef32_pk_f16_fp4 v16, v18, 1.0 op_sel:[1,1,0]
	v_pk_fma_f16 v106, v16, v73, v50
	v_cvt_scalef32_pk_f16_fp4 v16, v19, 1.0
	v_pk_fma_f16 v103, v16, v73, v103
	v_cvt_scalef32_pk_f16_fp4 v16, v19, 1.0 op_sel:[1,0,0]
	v_pk_fma_f16 v104, v16, v73, v104
	v_cvt_scalef32_pk_f16_fp4 v16, v19, 1.0 op_sel:[0,1,0]
	v_pk_fma_f16 v105, v16, v73, v105
	v_cvt_scalef32_pk_f16_fp4 v16, v19, 1.0 op_sel:[1,1,0]
	s_waitcnt lgkmcnt(1)
	v_add_u32_e32 v76, v76, v96
	v_pk_fma_f16 v73, v16, v73, v51
	v_add_u32_e32 v77, v77, v96
	global_load_dwordx4 v[48:51], v76, s[12:13]
	global_load_dwordx4 v[16:19], v77, s[12:13]
	s_waitcnt vmcnt(16)
	v_cvt_scalef32_pk_f16_fp4 v76, v52, 1.0
	v_pk_fma_f16 v72, v76, v74, v72
	v_cvt_scalef32_pk_f16_fp4 v76, v52, 1.0 op_sel:[1,0,0]
	v_cvt_scalef32_pk_f16_fp4 v77, v52, 1.0 op_sel:[0,1,0]
	v_cvt_scalef32_pk_f16_fp4 v52, v52, 1.0 op_sel:[1,1,0]
	v_pk_fma_f16 v76, v76, v74, v80
	v_pk_fma_f16 v52, v52, v74, v82
	v_cvt_scalef32_pk_f16_fp4 v80, v53, 1.0
	v_cvt_scalef32_pk_f16_fp4 v82, v53, 1.0 op_sel:[0,1,0]
	v_pk_fma_f16 v77, v77, v74, v81
	v_pk_fma_f16 v80, v80, v74, v83
	v_cvt_scalef32_pk_f16_fp4 v81, v53, 1.0 op_sel:[1,0,0]
	v_pk_fma_f16 v82, v82, v74, v99
	v_cvt_scalef32_pk_f16_fp4 v53, v53, 1.0 op_sel:[1,1,0]
	v_cvt_scalef32_pk_f16_fp4 v83, v54, 1.0
	v_cvt_scalef32_pk_f16_fp4 v99, v54, 1.0 op_sel:[0,1,0]
	v_pk_fma_f16 v53, v53, v74, v100
	v_pk_fma_f16 v83, v83, v74, v101
	v_pk_fma_f16 v97, v99, v74, v97
	v_cvt_scalef32_pk_f16_fp4 v99, v55, 1.0
	v_cvt_scalef32_pk_f16_fp4 v100, v55, 1.0 op_sel:[1,0,0]
	v_cvt_scalef32_pk_f16_fp4 v101, v55, 1.0 op_sel:[0,1,0]
	v_cvt_scalef32_pk_f16_fp4 v55, v55, 1.0 op_sel:[1,1,0]
	v_pk_fma_f16 v81, v81, v74, v98
	v_cvt_scalef32_pk_f16_fp4 v98, v54, 1.0 op_sel:[1,0,0]
	v_cvt_scalef32_pk_f16_fp4 v54, v54, 1.0 op_sel:[1,1,0]
	v_pk_fma_f16 v55, v55, v74, v73
	s_waitcnt vmcnt(15)
; __device__ __forceinline__ void p8_peer_gather(Frame& F) {
;     ...
;             for (int i = 0; i < 16; ++i) { const h16x2 cf2 = __builtin_bit_cast(h16x2, cc[i]);
; #pragma unroll
;                 for (int w = 0; w < 4; ++w) { ya[4 * w] += cf2 * __builtin_amdgcn_cvt_scalef32_pk_f16_fp4(d[i][w], 1.0f, 0); ya[4 * w + 1] += cf2 * __builtin_amdgcn_cvt_scalef32_pk_f16_fp4(d[i][w], 1.0f, 1);
;                     ya[4 * w + 2] += cf2 * __builtin_amdgcn_cvt_scalef32_pk_f16_fp4(d[i][w], 1.0f, 2); ya[4 * w + 3] += cf2 * __builtin_amdgcn_cvt_scalef32_pk_f16_fp4(d[i][w], 1.0f, 3); }
;                 d[i] = *(const v4u*)(VQ + (size_t)(idx_s[nj * 128 + pg * 16 + i] + noff)); }
	v_cvt_scalef32_pk_f16_fp4 v73, v20, 1.0
	v_pk_fma_f16 v98, v98, v74, v102
	v_pk_fma_f16 v54, v54, v74, v106
	v_pk_fma_f16 v99, v99, v74, v103
	v_pk_fma_f16 v100, v100, v74, v104
	v_pk_fma_f16 v101, v101, v74, v105
	v_pk_fma_f16 v72, v73, v75, v72
	v_cvt_scalef32_pk_f16_fp4 v73, v20, 1.0 op_sel:[1,0,0]
	v_cvt_scalef32_pk_f16_fp4 v74, v20, 1.0 op_sel:[0,1,0]
	v_cvt_scalef32_pk_f16_fp4 v20, v20, 1.0 op_sel:[1,1,0]
	v_pk_fma_f16 v73, v73, v75, v76
	v_pk_fma_f16 v76, v20, v75, v52
	v_cvt_scalef32_pk_f16_fp4 v20, v21, 1.0
	v_pk_fma_f16 v74, v74, v75, v77
	v_pk_fma_f16 v77, v20, v75, v80
	v_cvt_scalef32_pk_f16_fp4 v20, v21, 1.0 op_sel:[1,0,0]
	v_pk_fma_f16 v80, v20, v75, v81
	v_cvt_scalef32_pk_f16_fp4 v20, v21, 1.0 op_sel:[0,1,0]
	v_pk_fma_f16 v81, v20, v75, v82
	v_cvt_scalef32_pk_f16_fp4 v20, v21, 1.0 op_sel:[1,1,0]
	v_pk_fma_f16 v82, v20, v75, v53
	v_cvt_scalef32_pk_f16_fp4 v20, v22, 1.0
	v_pk_fma_f16 v83, v20, v75, v83
	v_cvt_scalef32_pk_f16_fp4 v20, v22, 1.0 op_sel:[1,0,0]
	v_pk_fma_f16 v98, v20, v75, v98
	v_cvt_scalef32_pk_f16_fp4 v20, v22, 1.0 op_sel:[0,1,0]
	v_pk_fma_f16 v97, v20, v75, v97
	v_cvt_scalef32_pk_f16_fp4 v20, v22, 1.0 op_sel:[1,1,0]
	v_pk_fma_f16 v102, v20, v75, v54
	v_cvt_scalef32_pk_f16_fp4 v20, v23, 1.0
	v_pk_fma_f16 v99, v20, v75, v99
	v_cvt_scalef32_pk_f16_fp4 v20, v23, 1.0 op_sel:[1,0,0]
	v_pk_fma_f16 v100, v20, v75, v100
	v_cvt_scalef32_pk_f16_fp4 v20, v23, 1.0 op_sel:[0,1,0]
	v_pk_fma_f16 v101, v20, v75, v101
	v_cvt_scalef32_pk_f16_fp4 v20, v23, 1.0 op_sel:[1,1,0]
	v_add_u32_e32 v78, v78, v96
	v_pk_fma_f16 v75, v20, v75, v55
	v_add_u32_e32 v79, v79, v96
	global_load_dwordx4 v[52:55], v78, s[12:13]
	global_load_dwordx4 v[20:23], v79, s[12:13]
	s_waitcnt vmcnt(16)
	v_cvt_scalef32_pk_f16_fp4 v78, v56, 1.0
	v_pk_fma_f16 v72, v78, v64, v72
	v_cvt_scalef32_pk_f16_fp4 v78, v56, 1.0 op_sel:[1,0,0]
	v_pk_fma_f16 v73, v78, v64, v73
	v_cvt_scalef32_pk_f16_fp4 v78, v56, 1.0 op_sel:[0,1,0]
	v_cvt_scalef32_pk_f16_fp4 v56, v56, 1.0 op_sel:[1,1,0]
	v_pk_fma_f16 v74, v78, v64, v74
	v_pk_fma_f16 v56, v56, v64, v76
	v_cvt_scalef32_pk_f16_fp4 v76, v57, 1.0
	v_cvt_scalef32_pk_f16_fp4 v78, v57, 1.0 op_sel:[0,1,0]
	v_pk_fma_f16 v76, v76, v64, v77
	v_cvt_scalef32_pk_f16_fp4 v77, v57, 1.0 op_sel:[1,0,0]
	v_pk_fma_f16 v78, v78, v64, v81
	v_cvt_scalef32_pk_f16_fp4 v57, v57, 1.0 op_sel:[1,1,0]
	v_cvt_scalef32_pk_f16_fp4 v79, v58, 1.0
	v_cvt_scalef32_pk_f16_fp4 v81, v58, 1.0 op_sel:[0,1,0]
	v_pk_fma_f16 v77, v77, v64, v80
	v_pk_fma_f16 v57, v57, v64, v82
	v_pk_fma_f16 v79, v79, v64, v83
	v_cvt_scalef32_pk_f16_fp4 v80, v58, 1.0 op_sel:[1,0,0]
	v_pk_fma_f16 v81, v81, v64, v97
	v_cvt_scalef32_pk_f16_fp4 v58, v58, 1.0 op_sel:[1,1,0]
	v_cvt_scalef32_pk_f16_fp4 v82, v59, 1.0
	v_cvt_scalef32_pk_f16_fp4 v83, v59, 1.0 op_sel:[1,0,0]
	v_cvt_scalef32_pk_f16_fp4 v97, v59, 1.0 op_sel:[0,1,0]
	v_cvt_scalef32_pk_f16_fp4 v59, v59, 1.0 op_sel:[1,1,0]
	v_pk_fma_f16 v80, v80, v64, v98
	v_pk_fma_f16 v58, v58, v64, v102
	v_pk_fma_f16 v82, v82, v64, v99
	v_pk_fma_f16 v83, v83, v64, v100
	v_pk_fma_f16 v97, v97, v64, v101
	v_pk_fma_f16 v59, v59, v64, v75
	s_waitcnt vmcnt(15)
	v_cvt_scalef32_pk_f16_fp4 v64, v32, 1.0
	v_pk_fma_f16 v64, v64, v65, v72
	v_cvt_scalef32_pk_f16_fp4 v72, v32, 1.0 op_sel:[1,0,0]
	v_pk_fma_f16 v72, v72, v65, v73
	v_cvt_scalef32_pk_f16_fp4 v73, v32, 1.0 op_sel:[0,1,0]
	v_cvt_scalef32_pk_f16_fp4 v32, v32, 1.0 op_sel:[1,1,0]
	v_pk_fma_f16 v73, v73, v65, v74
	v_pk_fma_f16 v74, v32, v65, v56
	v_cvt_scalef32_pk_f16_fp4 v32, v33, 1.0
	v_pk_fma_f16 v75, v32, v65, v76
	v_cvt_scalef32_pk_f16_fp4 v32, v33, 1.0 op_sel:[1,0,0]
	v_pk_fma_f16 v76, v32, v65, v77
	v_cvt_scalef32_pk_f16_fp4 v32, v33, 1.0 op_sel:[0,1,0]
	v_pk_fma_f16 v77, v32, v65, v78
	v_cvt_scalef32_pk_f16_fp4 v32, v33, 1.0 op_sel:[1,1,0]
	v_pk_fma_f16 v78, v32, v65, v57
	v_cvt_scalef32_pk_f16_fp4 v32, v34, 1.0
	v_pk_fma_f16 v79, v32, v65, v79
	v_cvt_scalef32_pk_f16_fp4 v32, v34, 1.0 op_sel:[1,0,0]
	v_pk_fma_f16 v80, v32, v65, v80
	v_cvt_scalef32_pk_f16_fp4 v32, v34, 1.0 op_sel:[0,1,0]
	v_pk_fma_f16 v81, v32, v65, v81
	v_cvt_scalef32_pk_f16_fp4 v32, v34, 1.0 op_sel:[1,1,0]
	v_pk_fma_f16 v98, v32, v65, v58
	v_cvt_scalef32_pk_f16_fp4 v32, v35, 1.0
	v_pk_fma_f16 v82, v32, v65, v82
	v_cvt_scalef32_pk_f16_fp4 v32, v35, 1.0 op_sel:[1,0,0]
	v_pk_fma_f16 v83, v32, v65, v83
	v_cvt_scalef32_pk_f16_fp4 v32, v35, 1.0 op_sel:[0,1,0]
	v_pk_fma_f16 v97, v32, v65, v97
	v_cvt_scalef32_pk_f16_fp4 v32, v35, 1.0 op_sel:[1,1,0]
	s_waitcnt lgkmcnt(0)
; __device__ __forceinline__ float xor8(float v) { return dppf<0x128>(v); }
; __device__ __forceinline__ float xor16(float v) { return __builtin_bit_cast(float, __builtin_amdgcn_ds_swizzle(__builtin_bit_cast(int, v), 0x401F)); }
; __device__ __forceinline__ void p8_peer_gather(Frame& F) {
;     ...
;             for (int i = 0; i < 16; ++i) { const h16x2 cf2 = __builtin_bit_cast(h16x2, cc[i]);
; #pragma unroll
;                 for (int w = 0; w < 4; ++w) { ya[4 * w] += cf2 * __builtin_amdgcn_cvt_scalef32_pk_f16_fp4(d[i][w], 1.0f, 0); ya[4 * w + 1] += cf2 * __builtin_amdgcn_cvt_scalef32_pk_f16_fp4(d[i][w], 1.0f, 1);
;                     ya[4 * w + 2] += cf2 * __builtin_amdgcn_cvt_scalef32_pk_f16_fp4(d[i][w], 1.0f, 2); ya[4 * w + 3] += cf2 * __builtin_amdgcn_cvt_scalef32_pk_f16_fp4(d[i][w], 1.0f, 3); }
;                 d[i] = *(const v4u*)(VQ + (size_t)(idx_s[nj * 128 + pg * 16 + i] + noff)); }
;             h16x2 tt[8];
; #pragma unroll
;             for (int e = 0; e < 8; ++e) {
;                 const auto rr = __builtin_amdgcn_permlane32_swap(__builtin_bit_cast(unsigned, ya[e]), __builtin_bit_cast(unsigned, ya[e + 8]), false, false);
;                 h16x2 t = __builtin_bit_cast(h16x2, (unsigned)rr[0]) + __builtin_bit_cast(h16x2, (unsigned)rr[1]);
;                 t += __builtin_bit_cast(h16x2, xor16(__builtin_bit_cast(float, t)));
;                 t += __builtin_bit_cast(h16x2, xor8(__builtin_bit_cast(float, t)));
;                 tt[e] = t; }
;             const int kq = pg & 3;
;             const h16x2 ta = kq == 0 ? tt[0] : kq == 1 ? tt[2] : kq == 2 ? tt[4] : tt[6], tb = kq == 0 ? tt[1] : kq == 1 ? tt[3] : kq == 2 ? tt[5] : tt[7];
	v_add_u32_e32 v68, v68, v96
	v_pk_fma_f16 v65, v32, v65, v59
	v_add_u32_e32 v69, v69, v96
	global_load_dwordx4 v[56:59], v68, s[12:13]
	global_load_dwordx4 v[32:35], v69, s[12:13]
	s_waitcnt vmcnt(16)
	v_cvt_scalef32_pk_f16_fp4 v68, v60, 1.0
	v_add_u32_e32 v70, v70, v96
	v_pk_fma_f16 v64, v68, v66, v64
	v_cvt_scalef32_pk_f16_fp4 v68, v60, 1.0 op_sel:[1,0,0]
	v_cvt_scalef32_pk_f16_fp4 v69, v60, 1.0 op_sel:[0,1,0]
	v_cvt_scalef32_pk_f16_fp4 v99, v60, 1.0 op_sel:[1,1,0]
	v_cvt_scalef32_pk_f16_fp4 v100, v61, 1.0
	v_cvt_scalef32_pk_f16_fp4 v101, v61, 1.0 op_sel:[1,0,0]
	v_cvt_scalef32_pk_f16_fp4 v102, v61, 1.0 op_sel:[0,1,0]
	v_cvt_scalef32_pk_f16_fp4 v103, v61, 1.0 op_sel:[1,1,0]
	v_cvt_scalef32_pk_f16_fp4 v104, v62, 1.0
	v_cvt_scalef32_pk_f16_fp4 v105, v62, 1.0 op_sel:[1,0,0]
	v_cvt_scalef32_pk_f16_fp4 v106, v62, 1.0 op_sel:[0,1,0]
	v_cvt_scalef32_pk_f16_fp4 v107, v62, 1.0 op_sel:[1,1,0]
	v_cvt_scalef32_pk_f16_fp4 v108, v63, 1.0
	v_cvt_scalef32_pk_f16_fp4 v109, v63, 1.0 op_sel:[1,0,0]
	v_cvt_scalef32_pk_f16_fp4 v110, v63, 1.0 op_sel:[0,1,0]
	v_cvt_scalef32_pk_f16_fp4 v111, v63, 1.0 op_sel:[1,1,0]
	s_waitcnt vmcnt(15)
	v_cvt_scalef32_pk_f16_fp4 v112, v40, 1.0
	v_cvt_scalef32_pk_f16_fp4 v113, v40, 1.0 op_sel:[1,0,0]
	v_cvt_scalef32_pk_f16_fp4 v114, v40, 1.0 op_sel:[0,1,0]
	v_cvt_scalef32_pk_f16_fp4 v115, v40, 1.0 op_sel:[1,1,0]
	v_cvt_scalef32_pk_f16_fp4 v116, v41, 1.0
	v_cvt_scalef32_pk_f16_fp4 v117, v41, 1.0 op_sel:[1,0,0]
	v_cvt_scalef32_pk_f16_fp4 v118, v41, 1.0 op_sel:[0,1,0]
	v_cvt_scalef32_pk_f16_fp4 v119, v41, 1.0 op_sel:[1,1,0]
	v_cvt_scalef32_pk_f16_fp4 v120, v42, 1.0
	v_cvt_scalef32_pk_f16_fp4 v121, v42, 1.0 op_sel:[1,0,0]
	v_cvt_scalef32_pk_f16_fp4 v122, v42, 1.0 op_sel:[0,1,0]
	v_cvt_scalef32_pk_f16_fp4 v123, v42, 1.0 op_sel:[1,1,0]
	v_cvt_scalef32_pk_f16_fp4 v124, v43, 1.0
	v_cvt_scalef32_pk_f16_fp4 v125, v43, 1.0 op_sel:[1,0,0]
	v_cvt_scalef32_pk_f16_fp4 v126, v43, 1.0 op_sel:[0,1,0]
	v_cvt_scalef32_pk_f16_fp4 v127, v43, 1.0 op_sel:[1,1,0]
	v_add_u32_e32 v71, v71, v96
	global_load_dwordx4 v[60:63], v70, s[12:13]
	global_load_dwordx4 v[40:43], v71, s[12:13]
	v_pk_fma_f16 v68, v68, v66, v72
	v_pk_fma_f16 v69, v69, v66, v73
	v_pk_fma_f16 v70, v99, v66, v74
	v_pk_fma_f16 v71, v100, v66, v75
	v_pk_fma_f16 v72, v101, v66, v76
	v_pk_fma_f16 v73, v102, v66, v77
	v_pk_fma_f16 v75, v104, v66, v79
	v_pk_fma_f16 v74, v103, v66, v78
	v_pk_fma_f16 v76, v105, v66, v80
	v_pk_fma_f16 v77, v106, v66, v81
	v_pk_fma_f16 v78, v107, v66, v98
	v_pk_fma_f16 v79, v108, v66, v82
	v_pk_fma_f16 v80, v109, v66, v83
	v_pk_fma_f16 v81, v110, v66, v97
	v_pk_fma_f16 v65, v111, v66, v65
	v_pk_fma_f16 v64, v112, v67, v64
	v_pk_fma_f16 v66, v113, v67, v68
	v_pk_fma_f16 v68, v114, v67, v69
	v_pk_fma_f16 v69, v115, v67, v70
	v_pk_fma_f16 v70, v116, v67, v71
	v_pk_fma_f16 v71, v117, v67, v72
	v_pk_fma_f16 v72, v118, v67, v73
	v_pk_fma_f16 v73, v120, v67, v75
	v_pk_fma_f16 v82, v119, v67, v74
	v_pk_fma_f16 v74, v121, v67, v76
	v_pk_fma_f16 v76, v123, v67, v78
	v_pk_fma_f16 v75, v122, v67, v77
	v_pk_fma_f16 v83, v127, v67, v65
	v_pk_fma_f16 v77, v124, v67, v79
	v_pk_fma_f16 v80, v125, v67, v80
	v_pk_fma_f16 v81, v126, v67, v81
	v_permlane32_swap_b32_e32 v64, v73
	v_permlane32_swap_b32_e32 v66, v74
	v_permlane32_swap_b32_e32 v68, v75
	v_permlane32_swap_b32_e32 v69, v76
	v_permlane32_swap_b32_e32 v70, v77
	v_permlane32_swap_b32_e32 v71, v80
	v_permlane32_swap_b32_e32 v72, v81
	v_permlane32_swap_b32_e32 v82, v83
	v_pk_add_f16 v64, v64, v73
	v_pk_add_f16 v66, v66, v74
	v_pk_add_f16 v68, v68, v75
	v_pk_add_f16 v69, v69, v76
	v_pk_add_f16 v70, v70, v77
	v_pk_add_f16 v71, v71, v80
	v_pk_add_f16 v72, v72, v81
	v_pk_add_f16 v82, v82, v83
	v_permlane16_swap_b32_e32 v64, v70
	v_permlane16_swap_b32_e32 v66, v71
	v_permlane16_swap_b32_e32 v68, v72
	v_permlane16_swap_b32_e32 v69, v82
	v_pk_add_f16 v64, v64, v70
	v_pk_add_f16 v66, v66, v71
	v_pk_add_f16 v68, v68, v72
	v_pk_add_f16 v69, v69, v82
	v_cndmask_b32_e64 v73, v68, v64, s[42:43]
	v_cndmask_b32_e64 v74, v69, v66, s[42:43]
	v_cndmask_b32_e64 v75, v64, v68, s[42:43]
	v_cndmask_b32_e64 v76, v66, v69, s[42:43]
	v_mov_b32_dpp v77, v73 row_ror:8 row_mask:0xf bank_mask:0xf bound_ctrl:1
	v_mov_b32_dpp v80, v74 row_ror:8 row_mask:0xf bank_mask:0xf bound_ctrl:1
	v_pk_add_f16 v68, v75, v77
	v_pk_add_f16 v69, v76, v80
	s_branch .LBB0_2585
